# phase-0 pool-weight fold rewritten: the 128-step d reduction split over the 8 waves (n-half x d-quarter, 16-byte loads, all 32 loads of a wave in flight) and combined through LDS, instead of one 128-l
# speedup vs baseline: 1.0049x; 1.0031x over previous
.LBB0_65:
	s_or_b64 exec, exec, s[20:21]
	v_mov_b32_e32 v3, 0
	s_mov_b32 s0, 0x20000
	v_cmp_gt_i32_e32 vcc, s0, v0
	s_waitcnt vmcnt(1)
	v_readlane_b32 s13, v247, 31
	v_readlane_b32 s12, v247, 30
	s_waitcnt vmcnt(0)
	v_readlane_b32 s15, v247, 33
	v_readlane_b32 s14, v247, 32
	s_and_saveexec_b64 s[16:17], vcc
	s_cbranch_execz .LBB0_70
	s_cmpk_lg_i32 s56, 0x100
	s_cbranch_scc1 .Lpf3_generic
	v_mbcnt_lo_u32_b32 v1, -1, 0
	v_mbcnt_hi_u32_b32 v1, -1, v1
	v_readlane_b32 s0, v246, 6
	s_lshl_b32 s0, s0, 9
	s_lshr_b32 s1, s0, 15
	s_bfe_u32 s9, s0, 0x5000a
	s_and_b32 s18, s0, 0x3ff
	s_and_b32 s19, s94, 1
	s_lshr_b32 s22, s94, 1
	s_lshl_b32 s30, s1, 16
	s_lshl_b32 s31, s9, 11
	s_add_i32 s30, s30, s31
	s_add_u32 s24, s12, s30
	s_addc_u32 s25, s13, 0
	s_lshl_b32 s30, s1, 9
	s_add_u32 s26, s14, s30
	s_addc_u32 s27, s15, 0
	v_lshlrev_b32_e32 v61, 2, v1
	s_lshl_b32 s23, s94, 14
	v_add_u32_e32 v62, s23, v61
	s_lshl_b32 s30, s22, 7
	s_add_i32 s30, s30, s23
	v_mov_b32_e32 v59, s30
	global_load_dword v14, v61, s[24:25]
	global_load_dword v15, v61, s[24:25] offset:256
	global_load_dword v16, v61, s[24:25] offset:512
	global_load_dword v17, v61, s[24:25] offset:768
	global_load_dword v18, v61, s[24:25] offset:1024
	global_load_dword v19, v61, s[24:25] offset:1280
	global_load_dword v20, v61, s[24:25] offset:1536
	global_load_dword v21, v61, s[24:25] offset:1792
	global_load_dword v22, v61, s[26:27]
	global_load_dword v23, v61, s[26:27] offset:256
	v_readlane_b32 s28, v247, 36
	v_readlane_b32 s29, v247, 37
	s_lshl_b32 s30, s1, 7
	s_lshl_b32 s31, s22, 5
	s_add_i32 s30, s30, s31
	s_lshl_b32 s30, s30, 12
	s_add_u32 s28, s28, s30
	s_addc_u32 s29, s29, 0
	s_lshl_b32 s30, s19, 8
	s_add_i32 s30, s30, s18
	s_lshl_b32 s30, s30, 2
	v_lshlrev_b32_e32 v60, 4, v1
	v_add_u32_e32 v60, s30, v60
	s_nop 1
	global_load_dwordx4 v[64:67], v60, s[28:29]
	s_add_u32 s28, s28, 0x1000
	s_addc_u32 s29, s29, 0
	global_load_dwordx4 v[68:71], v60, s[28:29]
	s_add_u32 s28, s28, 0x1000
	s_addc_u32 s29, s29, 0
	global_load_dwordx4 v[72:75], v60, s[28:29]
	s_add_u32 s28, s28, 0x1000
	s_addc_u32 s29, s29, 0
	global_load_dwordx4 v[76:79], v60, s[28:29]
	s_add_u32 s28, s28, 0x1000
	s_addc_u32 s29, s29, 0
	global_load_dwordx4 v[80:83], v60, s[28:29]
	s_add_u32 s28, s28, 0x1000
	s_addc_u32 s29, s29, 0
	global_load_dwordx4 v[84:87], v60, s[28:29]
	s_add_u32 s28, s28, 0x1000
	s_addc_u32 s29, s29, 0
	global_load_dwordx4 v[88:91], v60, s[28:29]
	s_add_u32 s28, s28, 0x1000
	s_addc_u32 s29, s29, 0
	global_load_dwordx4 v[92:95], v60, s[28:29]
	s_add_u32 s28, s28, 0x1000
	s_addc_u32 s29, s29, 0
	global_load_dwordx4 v[96:99], v60, s[28:29]
	s_add_u32 s28, s28, 0x1000
	s_addc_u32 s29, s29, 0
	global_load_dwordx4 v[100:103], v60, s[28:29]
	s_add_u32 s28, s28, 0x1000
	s_addc_u32 s29, s29, 0
	global_load_dwordx4 v[104:107], v60, s[28:29]
	s_add_u32 s28, s28, 0x1000
	s_addc_u32 s29, s29, 0
	global_load_dwordx4 v[108:111], v60, s[28:29]
	s_add_u32 s28, s28, 0x1000
	s_addc_u32 s29, s29, 0
	global_load_dwordx4 v[112:115], v60, s[28:29]
	s_add_u32 s28, s28, 0x1000
	s_addc_u32 s29, s29, 0
	global_load_dwordx4 v[116:119], v60, s[28:29]
	s_add_u32 s28, s28, 0x1000
	s_addc_u32 s29, s29, 0
	global_load_dwordx4 v[120:123], v60, s[28:29]
	s_add_u32 s28, s28, 0x1000
	s_addc_u32 s29, s29, 0
	global_load_dwordx4 v[124:127], v60, s[28:29]
	s_add_u32 s28, s28, 0x1000
	s_addc_u32 s29, s29, 0
	global_load_dwordx4 v[128:131], v60, s[28:29]
	s_add_u32 s28, s28, 0x1000
	s_addc_u32 s29, s29, 0
	global_load_dwordx4 v[132:135], v60, s[28:29]
	s_add_u32 s28, s28, 0x1000
	s_addc_u32 s29, s29, 0
	global_load_dwordx4 v[136:139], v60, s[28:29]
	s_add_u32 s28, s28, 0x1000
	s_addc_u32 s29, s29, 0
	global_load_dwordx4 v[140:143], v60, s[28:29]
	s_add_u32 s28, s28, 0x1000
	s_addc_u32 s29, s29, 0
	global_load_dwordx4 v[144:147], v60, s[28:29]
	s_add_u32 s28, s28, 0x1000
	s_addc_u32 s29, s29, 0
	global_load_dwordx4 v[148:151], v60, s[28:29]
	s_add_u32 s28, s28, 0x1000
	s_addc_u32 s29, s29, 0
	global_load_dwordx4 v[152:155], v60, s[28:29]
	s_add_u32 s28, s28, 0x1000
	s_addc_u32 s29, s29, 0
	global_load_dwordx4 v[156:159], v60, s[28:29]
	s_add_u32 s28, s28, 0x1000
	s_addc_u32 s29, s29, 0
	global_load_dwordx4 v[160:163], v60, s[28:29]
	s_add_u32 s28, s28, 0x1000
	s_addc_u32 s29, s29, 0
	global_load_dwordx4 v[164:167], v60, s[28:29]
	s_add_u32 s28, s28, 0x1000
	s_addc_u32 s29, s29, 0
	global_load_dwordx4 v[168:171], v60, s[28:29]
	s_add_u32 s28, s28, 0x1000
	s_addc_u32 s29, s29, 0
	global_load_dwordx4 v[172:175], v60, s[28:29]
	s_add_u32 s28, s28, 0x1000
	s_addc_u32 s29, s29, 0
	global_load_dwordx4 v[176:179], v60, s[28:29]
	s_add_u32 s28, s28, 0x1000
	s_addc_u32 s29, s29, 0
	global_load_dwordx4 v[180:183], v60, s[28:29]
	s_add_u32 s28, s28, 0x1000
	s_addc_u32 s29, s29, 0
	global_load_dwordx4 v[184:187], v60, s[28:29]
	s_add_u32 s28, s28, 0x1000
	s_addc_u32 s29, s29, 0
	global_load_dwordx4 v[188:191], v60, s[28:29]
	s_add_u32 s28, s28, 0x1000
	s_addc_u32 s29, s29, 0
	s_waitcnt vmcnt(32)
	ds_write_b32 v62, v14
	ds_write_b32 v62, v15 offset:256
	ds_write_b32 v62, v16 offset:512
	ds_write_b32 v62, v17 offset:768
	ds_write_b32 v62, v18 offset:1024
	ds_write_b32 v62, v19 offset:1280
	ds_write_b32 v62, v20 offset:1536
	ds_write_b32 v62, v21 offset:1792
	ds_write_b32 v62, v22 offset:2048
	ds_write_b32 v62, v23 offset:2304
	s_waitcnt lgkmcnt(0)
	v_mov_b32_e32 v10, 0
	v_mov_b32_e32 v11, 0
	v_mov_b32_e32 v12, 0
	v_mov_b32_e32 v13, 0
	v_mov_b32_e32 v14, 0
	v_mov_b32_e32 v15, 0
	v_mov_b32_e32 v16, 0
	v_mov_b32_e32 v17, 0
	v_mov_b32_e32 v18, 0
	v_mov_b32_e32 v19, 0
	v_mov_b32_e32 v20, 0
	v_mov_b32_e32 v21, 0
	v_mov_b32_e32 v22, 0
	v_mov_b32_e32 v23, 0
	v_mov_b32_e32 v24, 0
	v_mov_b32_e32 v25, 0
	ds_read_b128 v[192:195], v59 offset:2048
	ds_read_b128 v[196:199], v59 offset:2064
	ds_read_b128 v[200:203], v59 offset:0
	ds_read_b128 v[204:207], v59 offset:16
	ds_read_b128 v[208:211], v59 offset:512
	ds_read_b128 v[212:215], v59 offset:528
	ds_read_b128 v[216:219], v59 offset:1024
	ds_read_b128 v[220:223], v59 offset:1040
	ds_read_b128 v[224:227], v59 offset:1536
	ds_read_b128 v[228:231], v59 offset:1552
	s_waitcnt vmcnt(24)
	s_waitcnt lgkmcnt(0)
	v_mul_f32_e32 v232, v192, v64
	v_mul_f32_e32 v233, v192, v65
	v_mul_f32_e32 v234, v192, v66
	v_mul_f32_e32 v235, v192, v67
	v_fmac_f32_e32 v10, v200, v232
	v_fmac_f32_e32 v14, v200, v233
	v_fmac_f32_e32 v18, v200, v234
	v_fmac_f32_e32 v22, v200, v235
	v_fmac_f32_e32 v11, v208, v232
	v_fmac_f32_e32 v15, v208, v233
	v_fmac_f32_e32 v19, v208, v234
	v_fmac_f32_e32 v23, v208, v235
	v_fmac_f32_e32 v12, v216, v232
	v_fmac_f32_e32 v16, v216, v233
	v_fmac_f32_e32 v20, v216, v234
	v_fmac_f32_e32 v24, v216, v235
	v_fmac_f32_e32 v13, v224, v232
	v_fmac_f32_e32 v17, v224, v233
	v_fmac_f32_e32 v21, v224, v234
	v_fmac_f32_e32 v25, v224, v235
	v_mul_f32_e32 v232, v193, v68
	v_mul_f32_e32 v233, v193, v69
	v_mul_f32_e32 v234, v193, v70
	v_mul_f32_e32 v235, v193, v71
	v_fmac_f32_e32 v10, v201, v232
	v_fmac_f32_e32 v14, v201, v233
	v_fmac_f32_e32 v18, v201, v234
	v_fmac_f32_e32 v22, v201, v235
	v_fmac_f32_e32 v11, v209, v232
	v_fmac_f32_e32 v15, v209, v233
	v_fmac_f32_e32 v19, v209, v234
	v_fmac_f32_e32 v23, v209, v235
	v_fmac_f32_e32 v12, v217, v232
	v_fmac_f32_e32 v16, v217, v233
	v_fmac_f32_e32 v20, v217, v234
	v_fmac_f32_e32 v24, v217, v235
	v_fmac_f32_e32 v13, v225, v232
	v_fmac_f32_e32 v17, v225, v233
	v_fmac_f32_e32 v21, v225, v234
	v_fmac_f32_e32 v25, v225, v235
	v_mul_f32_e32 v232, v194, v72
	v_mul_f32_e32 v233, v194, v73
	v_mul_f32_e32 v234, v194, v74
	v_mul_f32_e32 v235, v194, v75
	v_fmac_f32_e32 v10, v202, v232
	v_fmac_f32_e32 v14, v202, v233
	v_fmac_f32_e32 v18, v202, v234
	v_fmac_f32_e32 v22, v202, v235
	v_fmac_f32_e32 v11, v210, v232
	v_fmac_f32_e32 v15, v210, v233
	v_fmac_f32_e32 v19, v210, v234
	v_fmac_f32_e32 v23, v210, v235
	v_fmac_f32_e32 v12, v218, v232
	v_fmac_f32_e32 v16, v218, v233
	v_fmac_f32_e32 v20, v218, v234
	v_fmac_f32_e32 v24, v218, v235
	v_fmac_f32_e32 v13, v226, v232
	v_fmac_f32_e32 v17, v226, v233
	v_fmac_f32_e32 v21, v226, v234
	v_fmac_f32_e32 v25, v226, v235
	v_mul_f32_e32 v232, v195, v76
	v_mul_f32_e32 v233, v195, v77
	v_mul_f32_e32 v234, v195, v78
	v_mul_f32_e32 v235, v195, v79
	v_fmac_f32_e32 v10, v203, v232
	v_fmac_f32_e32 v14, v203, v233
	v_fmac_f32_e32 v18, v203, v234
	v_fmac_f32_e32 v22, v203, v235
	v_fmac_f32_e32 v11, v211, v232
	v_fmac_f32_e32 v15, v211, v233
	v_fmac_f32_e32 v19, v211, v234
	v_fmac_f32_e32 v23, v211, v235
	v_fmac_f32_e32 v12, v219, v232
	v_fmac_f32_e32 v16, v219, v233
	v_fmac_f32_e32 v20, v219, v234
	v_fmac_f32_e32 v24, v219, v235
	v_fmac_f32_e32 v13, v227, v232
	v_fmac_f32_e32 v17, v227, v233
	v_fmac_f32_e32 v21, v227, v234
	v_fmac_f32_e32 v25, v227, v235
	v_mul_f32_e32 v232, v196, v80
	v_mul_f32_e32 v233, v196, v81
	v_mul_f32_e32 v234, v196, v82
	v_mul_f32_e32 v235, v196, v83
	v_fmac_f32_e32 v10, v204, v232
	v_fmac_f32_e32 v14, v204, v233
	v_fmac_f32_e32 v18, v204, v234
	v_fmac_f32_e32 v22, v204, v235
	v_fmac_f32_e32 v11, v212, v232
	v_fmac_f32_e32 v15, v212, v233
	v_fmac_f32_e32 v19, v212, v234
	v_fmac_f32_e32 v23, v212, v235
	v_fmac_f32_e32 v12, v220, v232
	v_fmac_f32_e32 v16, v220, v233
	v_fmac_f32_e32 v20, v220, v234
	v_fmac_f32_e32 v24, v220, v235
	v_fmac_f32_e32 v13, v228, v232
	v_fmac_f32_e32 v17, v228, v233
	v_fmac_f32_e32 v21, v228, v234
	v_fmac_f32_e32 v25, v228, v235
	v_mul_f32_e32 v232, v197, v84
	v_mul_f32_e32 v233, v197, v85
	v_mul_f32_e32 v234, v197, v86
	v_mul_f32_e32 v235, v197, v87
	v_fmac_f32_e32 v10, v205, v232
	v_fmac_f32_e32 v14, v205, v233
	v_fmac_f32_e32 v18, v205, v234
	v_fmac_f32_e32 v22, v205, v235
	v_fmac_f32_e32 v11, v213, v232
	v_fmac_f32_e32 v15, v213, v233
	v_fmac_f32_e32 v19, v213, v234
	v_fmac_f32_e32 v23, v213, v235
	v_fmac_f32_e32 v12, v221, v232
	v_fmac_f32_e32 v16, v221, v233
	v_fmac_f32_e32 v20, v221, v234
	v_fmac_f32_e32 v24, v221, v235
	v_fmac_f32_e32 v13, v229, v232
	v_fmac_f32_e32 v17, v229, v233
	v_fmac_f32_e32 v21, v229, v234
	v_fmac_f32_e32 v25, v229, v235
	v_mul_f32_e32 v232, v198, v88
	v_mul_f32_e32 v233, v198, v89
	v_mul_f32_e32 v234, v198, v90
	v_mul_f32_e32 v235, v198, v91
	v_fmac_f32_e32 v10, v206, v232
	v_fmac_f32_e32 v14, v206, v233
	v_fmac_f32_e32 v18, v206, v234
	v_fmac_f32_e32 v22, v206, v235
	v_fmac_f32_e32 v11, v214, v232
	v_fmac_f32_e32 v15, v214, v233
	v_fmac_f32_e32 v19, v214, v234
	v_fmac_f32_e32 v23, v214, v235
	v_fmac_f32_e32 v12, v222, v232
	v_fmac_f32_e32 v16, v222, v233
	v_fmac_f32_e32 v20, v222, v234
	v_fmac_f32_e32 v24, v222, v235
	v_fmac_f32_e32 v13, v230, v232
	v_fmac_f32_e32 v17, v230, v233
	v_fmac_f32_e32 v21, v230, v234
	v_fmac_f32_e32 v25, v230, v235
	v_mul_f32_e32 v232, v199, v92
	v_mul_f32_e32 v233, v199, v93
	v_mul_f32_e32 v234, v199, v94
	v_mul_f32_e32 v235, v199, v95
	v_fmac_f32_e32 v10, v207, v232
	v_fmac_f32_e32 v14, v207, v233
	v_fmac_f32_e32 v18, v207, v234
	v_fmac_f32_e32 v22, v207, v235
	v_fmac_f32_e32 v11, v215, v232
	v_fmac_f32_e32 v15, v215, v233
	v_fmac_f32_e32 v19, v215, v234
	v_fmac_f32_e32 v23, v215, v235
	v_fmac_f32_e32 v12, v223, v232
	v_fmac_f32_e32 v16, v223, v233
	v_fmac_f32_e32 v20, v223, v234
	v_fmac_f32_e32 v24, v223, v235
	v_fmac_f32_e32 v13, v231, v232
	v_fmac_f32_e32 v17, v231, v233
	v_fmac_f32_e32 v21, v231, v234
	v_fmac_f32_e32 v25, v231, v235
	ds_read_b128 v[192:195], v59 offset:2080
	ds_read_b128 v[196:199], v59 offset:2096
	ds_read_b128 v[200:203], v59 offset:32
	ds_read_b128 v[204:207], v59 offset:48
	ds_read_b128 v[208:211], v59 offset:544
	ds_read_b128 v[212:215], v59 offset:560
	ds_read_b128 v[216:219], v59 offset:1056
	ds_read_b128 v[220:223], v59 offset:1072
	ds_read_b128 v[224:227], v59 offset:1568
	ds_read_b128 v[228:231], v59 offset:1584
	s_waitcnt vmcnt(16)
	s_waitcnt lgkmcnt(0)
	v_mul_f32_e32 v232, v192, v96
	v_mul_f32_e32 v233, v192, v97
	v_mul_f32_e32 v234, v192, v98
	v_mul_f32_e32 v235, v192, v99
	v_fmac_f32_e32 v10, v200, v232
	v_fmac_f32_e32 v14, v200, v233
	v_fmac_f32_e32 v18, v200, v234
	v_fmac_f32_e32 v22, v200, v235
	v_fmac_f32_e32 v11, v208, v232
	v_fmac_f32_e32 v15, v208, v233
	v_fmac_f32_e32 v19, v208, v234
	v_fmac_f32_e32 v23, v208, v235
	v_fmac_f32_e32 v12, v216, v232
	v_fmac_f32_e32 v16, v216, v233
	v_fmac_f32_e32 v20, v216, v234
	v_fmac_f32_e32 v24, v216, v235
	v_fmac_f32_e32 v13, v224, v232
	v_fmac_f32_e32 v17, v224, v233
	v_fmac_f32_e32 v21, v224, v234
	v_fmac_f32_e32 v25, v224, v235
	v_mul_f32_e32 v232, v193, v100
	v_mul_f32_e32 v233, v193, v101
	v_mul_f32_e32 v234, v193, v102
	v_mul_f32_e32 v235, v193, v103
	v_fmac_f32_e32 v10, v201, v232
	v_fmac_f32_e32 v14, v201, v233
	v_fmac_f32_e32 v18, v201, v234
	v_fmac_f32_e32 v22, v201, v235
	v_fmac_f32_e32 v11, v209, v232
	v_fmac_f32_e32 v15, v209, v233
	v_fmac_f32_e32 v19, v209, v234
	v_fmac_f32_e32 v23, v209, v235
	v_fmac_f32_e32 v12, v217, v232
	v_fmac_f32_e32 v16, v217, v233
	v_fmac_f32_e32 v20, v217, v234
	v_fmac_f32_e32 v24, v217, v235
	v_fmac_f32_e32 v13, v225, v232
	v_fmac_f32_e32 v17, v225, v233
	v_fmac_f32_e32 v21, v225, v234
	v_fmac_f32_e32 v25, v225, v235
	v_mul_f32_e32 v232, v194, v104
	v_mul_f32_e32 v233, v194, v105
	v_mul_f32_e32 v234, v194, v106
	v_mul_f32_e32 v235, v194, v107
	v_fmac_f32_e32 v10, v202, v232
	v_fmac_f32_e32 v14, v202, v233
	v_fmac_f32_e32 v18, v202, v234
	v_fmac_f32_e32 v22, v202, v235
	v_fmac_f32_e32 v11, v210, v232
	v_fmac_f32_e32 v15, v210, v233
	v_fmac_f32_e32 v19, v210, v234
	v_fmac_f32_e32 v23, v210, v235
	v_fmac_f32_e32 v12, v218, v232
	v_fmac_f32_e32 v16, v218, v233
	v_fmac_f32_e32 v20, v218, v234
	v_fmac_f32_e32 v24, v218, v235
	v_fmac_f32_e32 v13, v226, v232
	v_fmac_f32_e32 v17, v226, v233
	v_fmac_f32_e32 v21, v226, v234
	v_fmac_f32_e32 v25, v226, v235
	v_mul_f32_e32 v232, v195, v108
	v_mul_f32_e32 v233, v195, v109
	v_mul_f32_e32 v234, v195, v110
	v_mul_f32_e32 v235, v195, v111
	v_fmac_f32_e32 v10, v203, v232
	v_fmac_f32_e32 v14, v203, v233
	v_fmac_f32_e32 v18, v203, v234
	v_fmac_f32_e32 v22, v203, v235
	v_fmac_f32_e32 v11, v211, v232
	v_fmac_f32_e32 v15, v211, v233
	v_fmac_f32_e32 v19, v211, v234
	v_fmac_f32_e32 v23, v211, v235
	v_fmac_f32_e32 v12, v219, v232
	v_fmac_f32_e32 v16, v219, v233
	v_fmac_f32_e32 v20, v219, v234
	v_fmac_f32_e32 v24, v219, v235
	v_fmac_f32_e32 v13, v227, v232
	v_fmac_f32_e32 v17, v227, v233
	v_fmac_f32_e32 v21, v227, v234
	v_fmac_f32_e32 v25, v227, v235
	v_mul_f32_e32 v232, v196, v112
	v_mul_f32_e32 v233, v196, v113
	v_mul_f32_e32 v234, v196, v114
	v_mul_f32_e32 v235, v196, v115
	v_fmac_f32_e32 v10, v204, v232
	v_fmac_f32_e32 v14, v204, v233
	v_fmac_f32_e32 v18, v204, v234
	v_fmac_f32_e32 v22, v204, v235
	v_fmac_f32_e32 v11, v212, v232
	v_fmac_f32_e32 v15, v212, v233
	v_fmac_f32_e32 v19, v212, v234
	v_fmac_f32_e32 v23, v212, v235
	v_fmac_f32_e32 v12, v220, v232
	v_fmac_f32_e32 v16, v220, v233
	v_fmac_f32_e32 v20, v220, v234
	v_fmac_f32_e32 v24, v220, v235
	v_fmac_f32_e32 v13, v228, v232
	v_fmac_f32_e32 v17, v228, v233
	v_fmac_f32_e32 v21, v228, v234
	v_fmac_f32_e32 v25, v228, v235
	v_mul_f32_e32 v232, v197, v116
	v_mul_f32_e32 v233, v197, v117
	v_mul_f32_e32 v234, v197, v118
	v_mul_f32_e32 v235, v197, v119
	v_fmac_f32_e32 v10, v205, v232
	v_fmac_f32_e32 v14, v205, v233
	v_fmac_f32_e32 v18, v205, v234
	v_fmac_f32_e32 v22, v205, v235
	v_fmac_f32_e32 v11, v213, v232
	v_fmac_f32_e32 v15, v213, v233
	v_fmac_f32_e32 v19, v213, v234
	v_fmac_f32_e32 v23, v213, v235
	v_fmac_f32_e32 v12, v221, v232
	v_fmac_f32_e32 v16, v221, v233
	v_fmac_f32_e32 v20, v221, v234
	v_fmac_f32_e32 v24, v221, v235
	v_fmac_f32_e32 v13, v229, v232
	v_fmac_f32_e32 v17, v229, v233
	v_fmac_f32_e32 v21, v229, v234
	v_fmac_f32_e32 v25, v229, v235
	v_mul_f32_e32 v232, v198, v120
	v_mul_f32_e32 v233, v198, v121
	v_mul_f32_e32 v234, v198, v122
	v_mul_f32_e32 v235, v198, v123
	v_fmac_f32_e32 v10, v206, v232
	v_fmac_f32_e32 v14, v206, v233
	v_fmac_f32_e32 v18, v206, v234
	v_fmac_f32_e32 v22, v206, v235
	v_fmac_f32_e32 v11, v214, v232
	v_fmac_f32_e32 v15, v214, v233
	v_fmac_f32_e32 v19, v214, v234
	v_fmac_f32_e32 v23, v214, v235
	v_fmac_f32_e32 v12, v222, v232
	v_fmac_f32_e32 v16, v222, v233
	v_fmac_f32_e32 v20, v222, v234
	v_fmac_f32_e32 v24, v222, v235
	v_fmac_f32_e32 v13, v230, v232
	v_fmac_f32_e32 v17, v230, v233
	v_fmac_f32_e32 v21, v230, v234
	v_fmac_f32_e32 v25, v230, v235
	v_mul_f32_e32 v232, v199, v124
	v_mul_f32_e32 v233, v199, v125
	v_mul_f32_e32 v234, v199, v126
	v_mul_f32_e32 v235, v199, v127
	v_fmac_f32_e32 v10, v207, v232
	v_fmac_f32_e32 v14, v207, v233
	v_fmac_f32_e32 v18, v207, v234
	v_fmac_f32_e32 v22, v207, v235
	v_fmac_f32_e32 v11, v215, v232
	v_fmac_f32_e32 v15, v215, v233
	v_fmac_f32_e32 v19, v215, v234
	v_fmac_f32_e32 v23, v215, v235
	v_fmac_f32_e32 v12, v223, v232
	v_fmac_f32_e32 v16, v223, v233
	v_fmac_f32_e32 v20, v223, v234
	v_fmac_f32_e32 v24, v223, v235
	v_fmac_f32_e32 v13, v231, v232
	v_fmac_f32_e32 v17, v231, v233
	v_fmac_f32_e32 v21, v231, v234
	v_fmac_f32_e32 v25, v231, v235
	ds_read_b128 v[192:195], v59 offset:2112
	ds_read_b128 v[196:199], v59 offset:2128
	ds_read_b128 v[200:203], v59 offset:64
	ds_read_b128 v[204:207], v59 offset:80
	ds_read_b128 v[208:211], v59 offset:576
	ds_read_b128 v[212:215], v59 offset:592
	ds_read_b128 v[216:219], v59 offset:1088
	ds_read_b128 v[220:223], v59 offset:1104
	ds_read_b128 v[224:227], v59 offset:1600
	ds_read_b128 v[228:231], v59 offset:1616
	s_waitcnt vmcnt(8)
	s_waitcnt lgkmcnt(0)
	v_mul_f32_e32 v232, v192, v128
	v_mul_f32_e32 v233, v192, v129
	v_mul_f32_e32 v234, v192, v130
	v_mul_f32_e32 v235, v192, v131
	v_fmac_f32_e32 v10, v200, v232
	v_fmac_f32_e32 v14, v200, v233
	v_fmac_f32_e32 v18, v200, v234
	v_fmac_f32_e32 v22, v200, v235
	v_fmac_f32_e32 v11, v208, v232
	v_fmac_f32_e32 v15, v208, v233
	v_fmac_f32_e32 v19, v208, v234
	v_fmac_f32_e32 v23, v208, v235
	v_fmac_f32_e32 v12, v216, v232
	v_fmac_f32_e32 v16, v216, v233
	v_fmac_f32_e32 v20, v216, v234
	v_fmac_f32_e32 v24, v216, v235
	v_fmac_f32_e32 v13, v224, v232
	v_fmac_f32_e32 v17, v224, v233
	v_fmac_f32_e32 v21, v224, v234
	v_fmac_f32_e32 v25, v224, v235
	v_mul_f32_e32 v232, v193, v132
	v_mul_f32_e32 v233, v193, v133
	v_mul_f32_e32 v234, v193, v134
	v_mul_f32_e32 v235, v193, v135
	v_fmac_f32_e32 v10, v201, v232
	v_fmac_f32_e32 v14, v201, v233
	v_fmac_f32_e32 v18, v201, v234
	v_fmac_f32_e32 v22, v201, v235
	v_fmac_f32_e32 v11, v209, v232
	v_fmac_f32_e32 v15, v209, v233
	v_fmac_f32_e32 v19, v209, v234
	v_fmac_f32_e32 v23, v209, v235
	v_fmac_f32_e32 v12, v217, v232
	v_fmac_f32_e32 v16, v217, v233
	v_fmac_f32_e32 v20, v217, v234
	v_fmac_f32_e32 v24, v217, v235
	v_fmac_f32_e32 v13, v225, v232
	v_fmac_f32_e32 v17, v225, v233
	v_fmac_f32_e32 v21, v225, v234
	v_fmac_f32_e32 v25, v225, v235
	v_mul_f32_e32 v232, v194, v136
	v_mul_f32_e32 v233, v194, v137
	v_mul_f32_e32 v234, v194, v138
	v_mul_f32_e32 v235, v194, v139
	v_fmac_f32_e32 v10, v202, v232
	v_fmac_f32_e32 v14, v202, v233
	v_fmac_f32_e32 v18, v202, v234
	v_fmac_f32_e32 v22, v202, v235
	v_fmac_f32_e32 v11, v210, v232
	v_fmac_f32_e32 v15, v210, v233
	v_fmac_f32_e32 v19, v210, v234
	v_fmac_f32_e32 v23, v210, v235
	v_fmac_f32_e32 v12, v218, v232
	v_fmac_f32_e32 v16, v218, v233
	v_fmac_f32_e32 v20, v218, v234
	v_fmac_f32_e32 v24, v218, v235
	v_fmac_f32_e32 v13, v226, v232
	v_fmac_f32_e32 v17, v226, v233
	v_fmac_f32_e32 v21, v226, v234
	v_fmac_f32_e32 v25, v226, v235
	v_mul_f32_e32 v232, v195, v140
	v_mul_f32_e32 v233, v195, v141
	v_mul_f32_e32 v234, v195, v142
	v_mul_f32_e32 v235, v195, v143
	v_fmac_f32_e32 v10, v203, v232
	v_fmac_f32_e32 v14, v203, v233
	v_fmac_f32_e32 v18, v203, v234
	v_fmac_f32_e32 v22, v203, v235
	v_fmac_f32_e32 v11, v211, v232
	v_fmac_f32_e32 v15, v211, v233
	v_fmac_f32_e32 v19, v211, v234
	v_fmac_f32_e32 v23, v211, v235
	v_fmac_f32_e32 v12, v219, v232
	v_fmac_f32_e32 v16, v219, v233
	v_fmac_f32_e32 v20, v219, v234
	v_fmac_f32_e32 v24, v219, v235
	v_fmac_f32_e32 v13, v227, v232
	v_fmac_f32_e32 v17, v227, v233
	v_fmac_f32_e32 v21, v227, v234
	v_fmac_f32_e32 v25, v227, v235
	v_mul_f32_e32 v232, v196, v144
	v_mul_f32_e32 v233, v196, v145
	v_mul_f32_e32 v234, v196, v146
	v_mul_f32_e32 v235, v196, v147
	v_fmac_f32_e32 v10, v204, v232
	v_fmac_f32_e32 v14, v204, v233
	v_fmac_f32_e32 v18, v204, v234
	v_fmac_f32_e32 v22, v204, v235
	v_fmac_f32_e32 v11, v212, v232
	v_fmac_f32_e32 v15, v212, v233
	v_fmac_f32_e32 v19, v212, v234
	v_fmac_f32_e32 v23, v212, v235
	v_fmac_f32_e32 v12, v220, v232
	v_fmac_f32_e32 v16, v220, v233
	v_fmac_f32_e32 v20, v220, v234
	v_fmac_f32_e32 v24, v220, v235
	v_fmac_f32_e32 v13, v228, v232
	v_fmac_f32_e32 v17, v228, v233
	v_fmac_f32_e32 v21, v228, v234
	v_fmac_f32_e32 v25, v228, v235
	v_mul_f32_e32 v232, v197, v148
	v_mul_f32_e32 v233, v197, v149
	v_mul_f32_e32 v234, v197, v150
	v_mul_f32_e32 v235, v197, v151
	v_fmac_f32_e32 v10, v205, v232
	v_fmac_f32_e32 v14, v205, v233
	v_fmac_f32_e32 v18, v205, v234
	v_fmac_f32_e32 v22, v205, v235
	v_fmac_f32_e32 v11, v213, v232
	v_fmac_f32_e32 v15, v213, v233
	v_fmac_f32_e32 v19, v213, v234
	v_fmac_f32_e32 v23, v213, v235
	v_fmac_f32_e32 v12, v221, v232
	v_fmac_f32_e32 v16, v221, v233
	v_fmac_f32_e32 v20, v221, v234
	v_fmac_f32_e32 v24, v221, v235
	v_fmac_f32_e32 v13, v229, v232
	v_fmac_f32_e32 v17, v229, v233
	v_fmac_f32_e32 v21, v229, v234
	v_fmac_f32_e32 v25, v229, v235
	v_mul_f32_e32 v232, v198, v152
	v_mul_f32_e32 v233, v198, v153
	v_mul_f32_e32 v234, v198, v154
	v_mul_f32_e32 v235, v198, v155
	v_fmac_f32_e32 v10, v206, v232
	v_fmac_f32_e32 v14, v206, v233
	v_fmac_f32_e32 v18, v206, v234
	v_fmac_f32_e32 v22, v206, v235
	v_fmac_f32_e32 v11, v214, v232
	v_fmac_f32_e32 v15, v214, v233
	v_fmac_f32_e32 v19, v214, v234
	v_fmac_f32_e32 v23, v214, v235
	v_fmac_f32_e32 v12, v222, v232
	v_fmac_f32_e32 v16, v222, v233
	v_fmac_f32_e32 v20, v222, v234
	v_fmac_f32_e32 v24, v222, v235
	v_fmac_f32_e32 v13, v230, v232
	v_fmac_f32_e32 v17, v230, v233
	v_fmac_f32_e32 v21, v230, v234
	v_fmac_f32_e32 v25, v230, v235
	v_mul_f32_e32 v232, v199, v156
	v_mul_f32_e32 v233, v199, v157
	v_mul_f32_e32 v234, v199, v158
	v_mul_f32_e32 v235, v199, v159
	v_fmac_f32_e32 v10, v207, v232
	v_fmac_f32_e32 v14, v207, v233
	v_fmac_f32_e32 v18, v207, v234
	v_fmac_f32_e32 v22, v207, v235
	v_fmac_f32_e32 v11, v215, v232
	v_fmac_f32_e32 v15, v215, v233
	v_fmac_f32_e32 v19, v215, v234
	v_fmac_f32_e32 v23, v215, v235
	v_fmac_f32_e32 v12, v223, v232
	v_fmac_f32_e32 v16, v223, v233
	v_fmac_f32_e32 v20, v223, v234
	v_fmac_f32_e32 v24, v223, v235
	v_fmac_f32_e32 v13, v231, v232
	v_fmac_f32_e32 v17, v231, v233
	v_fmac_f32_e32 v21, v231, v234
	v_fmac_f32_e32 v25, v231, v235
	ds_read_b128 v[192:195], v59 offset:2144
	ds_read_b128 v[196:199], v59 offset:2160
	ds_read_b128 v[200:203], v59 offset:96
	ds_read_b128 v[204:207], v59 offset:112
	ds_read_b128 v[208:211], v59 offset:608
	ds_read_b128 v[212:215], v59 offset:624
	ds_read_b128 v[216:219], v59 offset:1120
	ds_read_b128 v[220:223], v59 offset:1136
	ds_read_b128 v[224:227], v59 offset:1632
	ds_read_b128 v[228:231], v59 offset:1648
	s_waitcnt vmcnt(0)
	s_waitcnt lgkmcnt(0)
	v_mul_f32_e32 v232, v192, v160
	v_mul_f32_e32 v233, v192, v161
	v_mul_f32_e32 v234, v192, v162
	v_mul_f32_e32 v235, v192, v163
	v_fmac_f32_e32 v10, v200, v232
	v_fmac_f32_e32 v14, v200, v233
	v_fmac_f32_e32 v18, v200, v234
	v_fmac_f32_e32 v22, v200, v235
	v_fmac_f32_e32 v11, v208, v232
	v_fmac_f32_e32 v15, v208, v233
	v_fmac_f32_e32 v19, v208, v234
	v_fmac_f32_e32 v23, v208, v235
	v_fmac_f32_e32 v12, v216, v232
	v_fmac_f32_e32 v16, v216, v233
	v_fmac_f32_e32 v20, v216, v234
	v_fmac_f32_e32 v24, v216, v235
	v_fmac_f32_e32 v13, v224, v232
	v_fmac_f32_e32 v17, v224, v233
	v_fmac_f32_e32 v21, v224, v234
	v_fmac_f32_e32 v25, v224, v235
	v_mul_f32_e32 v232, v193, v164
	v_mul_f32_e32 v233, v193, v165
	v_mul_f32_e32 v234, v193, v166
	v_mul_f32_e32 v235, v193, v167
	v_fmac_f32_e32 v10, v201, v232
	v_fmac_f32_e32 v14, v201, v233
	v_fmac_f32_e32 v18, v201, v234
	v_fmac_f32_e32 v22, v201, v235
	v_fmac_f32_e32 v11, v209, v232
	v_fmac_f32_e32 v15, v209, v233
	v_fmac_f32_e32 v19, v209, v234
	v_fmac_f32_e32 v23, v209, v235
	v_fmac_f32_e32 v12, v217, v232
	v_fmac_f32_e32 v16, v217, v233
	v_fmac_f32_e32 v20, v217, v234
	v_fmac_f32_e32 v24, v217, v235
	v_fmac_f32_e32 v13, v225, v232
	v_fmac_f32_e32 v17, v225, v233
	v_fmac_f32_e32 v21, v225, v234
	v_fmac_f32_e32 v25, v225, v235
	v_mul_f32_e32 v232, v194, v168
	v_mul_f32_e32 v233, v194, v169
	v_mul_f32_e32 v234, v194, v170
	v_mul_f32_e32 v235, v194, v171
	v_fmac_f32_e32 v10, v202, v232
	v_fmac_f32_e32 v14, v202, v233
	v_fmac_f32_e32 v18, v202, v234
	v_fmac_f32_e32 v22, v202, v235
	v_fmac_f32_e32 v11, v210, v232
	v_fmac_f32_e32 v15, v210, v233
	v_fmac_f32_e32 v19, v210, v234
	v_fmac_f32_e32 v23, v210, v235
	v_fmac_f32_e32 v12, v218, v232
	v_fmac_f32_e32 v16, v218, v233
	v_fmac_f32_e32 v20, v218, v234
	v_fmac_f32_e32 v24, v218, v235
	v_fmac_f32_e32 v13, v226, v232
	v_fmac_f32_e32 v17, v226, v233
	v_fmac_f32_e32 v21, v226, v234
	v_fmac_f32_e32 v25, v226, v235
	v_mul_f32_e32 v232, v195, v172
	v_mul_f32_e32 v233, v195, v173
	v_mul_f32_e32 v234, v195, v174
	v_mul_f32_e32 v235, v195, v175
	v_fmac_f32_e32 v10, v203, v232
	v_fmac_f32_e32 v14, v203, v233
	v_fmac_f32_e32 v18, v203, v234
	v_fmac_f32_e32 v22, v203, v235
	v_fmac_f32_e32 v11, v211, v232
	v_fmac_f32_e32 v15, v211, v233
	v_fmac_f32_e32 v19, v211, v234
	v_fmac_f32_e32 v23, v211, v235
	v_fmac_f32_e32 v12, v219, v232
	v_fmac_f32_e32 v16, v219, v233
	v_fmac_f32_e32 v20, v219, v234
	v_fmac_f32_e32 v24, v219, v235
	v_fmac_f32_e32 v13, v227, v232
	v_fmac_f32_e32 v17, v227, v233
	v_fmac_f32_e32 v21, v227, v234
	v_fmac_f32_e32 v25, v227, v235
	v_mul_f32_e32 v232, v196, v176
	v_mul_f32_e32 v233, v196, v177
	v_mul_f32_e32 v234, v196, v178
	v_mul_f32_e32 v235, v196, v179
	v_fmac_f32_e32 v10, v204, v232
	v_fmac_f32_e32 v14, v204, v233
	v_fmac_f32_e32 v18, v204, v234
	v_fmac_f32_e32 v22, v204, v235
	v_fmac_f32_e32 v11, v212, v232
	v_fmac_f32_e32 v15, v212, v233
	v_fmac_f32_e32 v19, v212, v234
	v_fmac_f32_e32 v23, v212, v235
	v_fmac_f32_e32 v12, v220, v232
	v_fmac_f32_e32 v16, v220, v233
	v_fmac_f32_e32 v20, v220, v234
	v_fmac_f32_e32 v24, v220, v235
	v_fmac_f32_e32 v13, v228, v232
	v_fmac_f32_e32 v17, v228, v233
	v_fmac_f32_e32 v21, v228, v234
	v_fmac_f32_e32 v25, v228, v235
	v_mul_f32_e32 v232, v197, v180
	v_mul_f32_e32 v233, v197, v181
	v_mul_f32_e32 v234, v197, v182
	v_mul_f32_e32 v235, v197, v183
	v_fmac_f32_e32 v10, v205, v232
	v_fmac_f32_e32 v14, v205, v233
	v_fmac_f32_e32 v18, v205, v234
	v_fmac_f32_e32 v22, v205, v235
	v_fmac_f32_e32 v11, v213, v232
	v_fmac_f32_e32 v15, v213, v233
	v_fmac_f32_e32 v19, v213, v234
	v_fmac_f32_e32 v23, v213, v235
	v_fmac_f32_e32 v12, v221, v232
	v_fmac_f32_e32 v16, v221, v233
	v_fmac_f32_e32 v20, v221, v234
	v_fmac_f32_e32 v24, v221, v235
	v_fmac_f32_e32 v13, v229, v232
	v_fmac_f32_e32 v17, v229, v233
	v_fmac_f32_e32 v21, v229, v234
	v_fmac_f32_e32 v25, v229, v235
	v_mul_f32_e32 v232, v198, v184
	v_mul_f32_e32 v233, v198, v185
	v_mul_f32_e32 v234, v198, v186
	v_mul_f32_e32 v235, v198, v187
	v_fmac_f32_e32 v10, v206, v232
	v_fmac_f32_e32 v14, v206, v233
	v_fmac_f32_e32 v18, v206, v234
	v_fmac_f32_e32 v22, v206, v235
	v_fmac_f32_e32 v11, v214, v232
	v_fmac_f32_e32 v15, v214, v233
	v_fmac_f32_e32 v19, v214, v234
	v_fmac_f32_e32 v23, v214, v235
	v_fmac_f32_e32 v12, v222, v232
	v_fmac_f32_e32 v16, v222, v233
	v_fmac_f32_e32 v20, v222, v234
	v_fmac_f32_e32 v24, v222, v235
	v_fmac_f32_e32 v13, v230, v232
	v_fmac_f32_e32 v17, v230, v233
	v_fmac_f32_e32 v21, v230, v234
	v_fmac_f32_e32 v25, v230, v235
	v_mul_f32_e32 v232, v199, v188
	v_mul_f32_e32 v233, v199, v189
	v_mul_f32_e32 v234, v199, v190
	v_mul_f32_e32 v235, v199, v191
	v_fmac_f32_e32 v10, v207, v232
	v_fmac_f32_e32 v14, v207, v233
	v_fmac_f32_e32 v18, v207, v234
	v_fmac_f32_e32 v22, v207, v235
	v_fmac_f32_e32 v11, v215, v232
	v_fmac_f32_e32 v15, v215, v233
	v_fmac_f32_e32 v19, v215, v234
	v_fmac_f32_e32 v23, v215, v235
	v_fmac_f32_e32 v12, v223, v232
	v_fmac_f32_e32 v16, v223, v233
	v_fmac_f32_e32 v20, v223, v234
	v_fmac_f32_e32 v24, v223, v235
	v_fmac_f32_e32 v13, v231, v232
	v_fmac_f32_e32 v17, v231, v233
	v_fmac_f32_e32 v21, v231, v234
	v_fmac_f32_e32 v25, v231, v235
	s_waitcnt lgkmcnt(0)
	s_barrier
	v_lshlrev_b32_e32 v58, 6, v1
	s_lshl_b32 s30, s22, 13
	s_lshl_b32 s31, s19, 12
	s_add_i32 s30, s30, s31
	v_add_u32_e32 v58, s30, v58
	ds_write_b128 v58, v[10:13]
	ds_write_b128 v58, v[14:17] offset:16
	ds_write_b128 v58, v[18:21] offset:32
	ds_write_b128 v58, v[22:25] offset:48
	s_waitcnt lgkmcnt(0)
	s_barrier
	s_lshl_b32 s30, s94, 10
	v_lshl_add_u32 v58, v1, 4, s30
	ds_read_b128 v[192:195], v58
	ds_read_b128 v[196:199], v58 offset:8192
	ds_read_b128 v[200:203], v58 offset:16384
	ds_read_b128 v[204:207], v58 offset:24576
	s_waitcnt lgkmcnt(0)
	v_pk_add_f32 v[192:193], v[192:193], v[196:197]
	v_pk_add_f32 v[194:195], v[194:195], v[198:199]
	v_pk_add_f32 v[192:193], v[192:193], v[200:201]
	v_pk_add_f32 v[194:195], v[194:195], v[202:203]
	v_pk_add_f32 v[192:193], v[192:193], v[204:205]
	v_pk_add_f32 v[194:195], v[194:195], v[206:207]
	s_lshl_b32 s30, s94, 6
	s_add_i32 s30, s30, s18
	v_add_u32_e32 v2, s30, v1
	v_lshlrev_b32_e32 v2, 11, v2
	s_lshr_b32 s31, s0, 10
	s_lshl_b32 s31, s31, 3
	s_add_u32 s34, s64, s31
	s_addc_u32 s35, s65, 0
	v_cvt_pk_bf16_f32 v6, v192, v193
	v_cvt_pk_bf16_f32 v7, v194, v195
	s_nop 1
	global_store_dwordx2 v2, v[6:7], s[34:35]
	s_waitcnt vmcnt(0) lgkmcnt(0)
	s_barrier
	s_branch .LBB0_70
.Lpf3_generic:
	s_add_u32 s10, s10, 0x1f000
	s_addc_u32 s11, s11, 0
	s_and_b32 s0, s93, 0x3c0
	v_add_u16_e32 v1, s0, v163
	v_readlane_b32 s0, v246, 6
	s_lshl_b32 s0, s0, 9
	s_mov_b64 s[18:19], 0
	v_add_u16_e32 v1, s0, v1
	s_mov_b32 s9, 0xfffe2000
	s_mov_b32 s24, 0xfffe3000
	s_mov_b32 s25, 0xfffe4000
	s_mov_b32 s26, 0xfffe5000
	s_mov_b32 s27, 0xfffe6000
	s_mov_b32 s28, 0xfffe7000
	s_mov_b32 s29, 0xfffe8000
	s_mov_b32 s30, 0xfffe9000
	s_mov_b32 s31, 0xfffea000
	s_mov_b32 s33, 0xfffeb000
	s_mov_b32 s34, 0xfffec000
	s_mov_b32 s35, 0xfffed000
	s_mov_b32 s36, 0xfffee000
	s_mov_b32 s37, 0xfffef000
	s_mov_b32 s38, 0xffff0000
	s_mov_b32 s39, 0xffff1000
	s_mov_b32 s42, 0xffff2000
	s_mov_b32 s43, 0xffff3000
	s_mov_b32 s44, 0xffff4000
	s_mov_b32 s45, 0xffff5000
	s_mov_b32 s46, 0xffff6000
	s_mov_b32 s47, 0xffff7000
	s_movk_i32 s48, 0x8000
	s_movk_i32 s49, 0x9000
	s_movk_i32 s62, 0xa000
	s_movk_i32 s63, 0xb000
	s_movk_i32 s67, 0xc000
	s_movk_i32 s68, 0xd000
	s_movk_i32 s69, 0xe000
	s_movk_i32 s70, 0xf000
	s_mov_b64 s[20:21], 0x20000
	s_mov_b32 s71, 0x1ffff
